# attention-phase weight-conversion (TR) units: the 8 global loads of each transpose iteration issued together (were load/wait/load/wait) for the W2out and Wout converters
# speedup vs baseline: 1.0093x; 1.0093x over previous
; #define LAS __attribute__((address_space(3)))
; __device__ __forceinline__ unsigned pk2(float lo, float hi) { return f2bf(lo) | (f2bf(hi) << 16); }
; __device__ __forceinline__ void tr_item(const float* __restrict__ W, int K, int N, bf16_t* __restrict__ WT, const float* __restrict__ gain, int mode, LAS float* scr, int item, int lane) {
;     ...
; #pragma unroll 8
;     for (int i = 0; i < 16; ++i) { const int kk = 4 * i + lk; const float g = gain ? gain[k0 + kk] * cs : cs; const f32x4 v = __builtin_nontemporal_load((const f32x4*)(W + (size_t)(k0 + kk) * N + src0 + ln));
;         LAS float* d = scr + kk * 65 + ln; d[0] = v.x * g; d[1] = v.y * g; d[2] = v.z * g; d[3] = v.w * g; }
;     asm volatile("s_waitcnt lgkmcnt(0)" ::: "memory");
;     const int c = lane >> 3, nn = lane & 7;
; #pragma unroll
;     for (int j = 0; j < 8; ++j) { const int n = nn + 8 * j; const LAS float* s = scr + (8 * c) * 65 + n;
;         v4u o; o.x = pk2(s[0 * 65], s[1 * 65]); o.y = pk2(s[2 * 65], s[3 * 65]); o.z = pk2(s[4 * 65], s[5 * 65]); o.w = pk2(s[6 * 65], s[7 * 65]);
;         *(v4u*)(WT + (size_t)(n0 + n) * K + k0 + 8 * c) = o; }
.LBB0_376:
	v_lshl_add_u64 v[64:65], v[62:63], 0, s[2:3]
	global_load_dwordx4 v[100:103], v[64:65], off nt
	v_lshl_add_u64 v[66:67], v[60:61], 0, s[2:3]
	global_load_dwordx4 v[104:107], v[66:67], off nt
	v_lshl_add_u64 v[64:65], v[58:59], 0, s[2:3]
	global_load_dwordx4 v[108:111], v[64:65], off nt
	v_lshl_add_u64 v[66:67], v[56:57], 0, s[2:3]
	global_load_dwordx4 v[112:115], v[66:67], off nt
	v_lshl_add_u64 v[64:65], v[54:55], 0, s[2:3]
	global_load_dwordx4 v[116:119], v[64:65], off nt
	v_lshl_add_u64 v[66:67], v[52:53], 0, s[2:3]
	global_load_dwordx4 v[120:123], v[66:67], off nt
	v_lshl_add_u64 v[64:65], v[50:51], 0, s[2:3]
	global_load_dwordx4 v[124:127], v[64:65], off nt
	v_lshl_add_u64 v[66:67], v[48:49], 0, s[2:3]
	global_load_dwordx4 v[128:131], v[66:67], off nt
	s_add_u32 s2, s2, 0x40000
	s_addc_u32 s3, s3, 0
	s_waitcnt vmcnt(7)
	ds_write2_b32 v0, v100, v101 offset1:1
	ds_write2_b32 v0, v102, v103 offset0:2 offset1:3
	s_waitcnt vmcnt(6)
	v_add_u32_e32 v68, 0x410, v0
	v_add_u32_e32 v64, 0x418, v0
	ds_write2_b32 v68, v104, v105 offset1:1
	ds_write2_b32 v64, v106, v107 offset1:1
	s_waitcnt vmcnt(5)
	v_add_u32_e32 v68, 0x820, v0
	v_add_u32_e32 v64, 0x828, v0
	ds_write2_b32 v68, v108, v109 offset1:1
	ds_write2_b32 v64, v110, v111 offset1:1
	s_waitcnt vmcnt(4)
	v_add_u32_e32 v68, 0xc30, v0
	v_add_u32_e32 v64, 0xc38, v0
	ds_write2_b32 v68, v112, v113 offset1:1
	ds_write2_b32 v64, v114, v115 offset1:1
	s_waitcnt vmcnt(3)
	v_add_u32_e32 v68, 0x1040, v0
	v_add_u32_e32 v64, 0x1048, v0
	ds_write2_b32 v68, v116, v117 offset1:1
	ds_write2_b32 v64, v118, v119 offset1:1
	s_waitcnt vmcnt(2)
	v_add_u32_e32 v68, 0x1450, v0
	v_add_u32_e32 v64, 0x1458, v0
	ds_write2_b32 v68, v120, v121 offset1:1
	ds_write2_b32 v64, v122, v123 offset1:1
	s_waitcnt vmcnt(1)
	v_add_u32_e32 v68, 0x1860, v0
	v_add_u32_e32 v64, 0x1868, v0
	ds_write2_b32 v68, v124, v125 offset1:1
	ds_write2_b32 v64, v126, v127 offset1:1
	s_waitcnt vmcnt(0)
	v_add_u32_e32 v68, 0x1c70, v0
	v_add_u32_e32 v64, 0x1c78, v0
	ds_write2_b32 v68, v128, v129 offset1:1
	ds_write2_b32 v64, v130, v131 offset1:1
	v_add_u32_e32 v0, 0x2080, v0
	s_cmp_lg_u32 s2, 0x80000
	s_cbranch_scc1 .LBB0_376
	s_waitcnt lgkmcnt(0)
	ds_read2_b32 v[48:49], v71 offset0:48 offset1:65
	ds_read2_b32 v[60:61], v71 offset1:8
	s_mov_b64 s[2:3], 0
	s_waitcnt lgkmcnt(1)
	v_bfe_u32 v50, v49, 16, 1
	v_add3_u32 v49, v49, v50, s31
	ds_read2_b32 v[62:63], v71 offset0:130 offset1:138
	ds_read2_b32 v[50:51], v71 offset0:178 offset1:195
	s_waitcnt lgkmcnt(2)
	v_bfe_u32 v0, v60, 16, 1
	v_add3_u32 v0, v60, v0, s31
	v_lshrrev_b32_e32 v0, 16, v0
	v_and_or_b32 v56, v49, s71, v0
	s_waitcnt lgkmcnt(1)
	v_bfe_u32 v0, v62, 16, 1
	v_add3_u32 v0, v62, v0, s31
	s_waitcnt lgkmcnt(0)
	v_bfe_u32 v49, v51, 16, 1
	v_lshrrev_b32_e32 v0, 16, v0
	v_add3_u32 v49, v51, v49, s31
	v_and_or_b32 v57, v49, s71, v0
	v_add_u32_e32 v49, 0x400, v71
	ds_read2_b32 v[64:65], v49 offset0:4 offset1:12
	ds_read2_b32 v[52:53], v49 offset0:52 offset1:69
	ds_read2_b32 v[66:67], v49 offset0:134 offset1:142
	ds_read2_b32 v[54:55], v49 offset0:182 offset1:199
	s_waitcnt lgkmcnt(3)
	v_bfe_u32 v0, v64, 16, 1
	v_add3_u32 v0, v64, v0, s31
	s_waitcnt lgkmcnt(2)
	v_bfe_u32 v51, v53, 16, 1
	v_lshrrev_b32_e32 v0, 16, v0
	v_add3_u32 v51, v53, v51, s31
	v_and_or_b32 v58, v51, s71, v0
	s_waitcnt lgkmcnt(1)
	v_bfe_u32 v0, v66, 16, 1
	v_add3_u32 v0, v66, v0, s31
	s_waitcnt lgkmcnt(0)
	v_bfe_u32 v51, v55, 16, 1
	v_lshrrev_b32_e32 v0, 16, v0
	v_add3_u32 v51, v55, v51, s31
	v_and_or_b32 v59, v51, s71, v0
	v_or_b32_e32 v0, s5, v3
	v_lshlrev_b32_e32 v0, 12, v0
	v_lshl_add_u64 v[68:69], v[12:13], 0, v[0:1]
	flat_store_dwordx4 v[68:69], v[56:59]
	ds_read2_b32 v[68:69], v71 offset0:73 offset1:81
	v_bfe_u32 v0, v61, 16, 1
	v_add3_u32 v0, v61, v0, s31
	ds_read2_b32 v[60:61], v71 offset0:203 offset1:211
	v_lshrrev_b32_e32 v0, 16, v0
	s_waitcnt lgkmcnt(0)
	v_bfe_u32 v51, v68, 16, 1
	v_add3_u32 v51, v68, v51, s31
	v_and_or_b32 v56, v51, s71, v0
	v_bfe_u32 v0, v63, 16, 1
	v_add3_u32 v0, v63, v0, s31
	v_bfe_u32 v51, v60, 16, 1
	ds_read2_b32 v[62:63], v49 offset0:77 offset1:85
	v_lshrrev_b32_e32 v0, 16, v0
	v_add3_u32 v51, v60, v51, s31
	v_and_or_b32 v57, v51, s71, v0
	v_bfe_u32 v0, v65, 16, 1
	v_add3_u32 v0, v65, v0, s31
	ds_read2_b32 v[64:65], v49 offset0:207 offset1:215
	s_waitcnt lgkmcnt(0)
	v_bfe_u32 v51, v62, 16, 1
	v_lshrrev_b32_e32 v0, 16, v0
	v_add3_u32 v51, v62, v51, s31
	v_and_or_b32 v58, v51, s71, v0
	v_bfe_u32 v0, v67, 16, 1
	v_add3_u32 v0, v67, v0, s31
	v_bfe_u32 v51, v64, 16, 1
	v_lshrrev_b32_e32 v0, 16, v0
	v_add3_u32 v51, v64, v51, s31
	v_and_or_b32 v59, v51, s71, v0
	v_or_b32_e32 v0, s5, v72
	v_lshlrev_b32_e32 v0, 12, v0
	v_lshl_add_u64 v[66:67], v[12:13], 0, v[0:1]
	flat_store_dwordx4 v[66:67], v[56:59]
	ds_read2_b32 v[66:67], v71 offset0:16 offset1:24
	v_bfe_u32 v51, v69, 16, 1
	v_add3_u32 v51, v69, v51, s31
	ds_read2_b32 v[68:69], v71 offset0:146 offset1:154
	s_waitcnt lgkmcnt(0)
	v_bfe_u32 v0, v66, 16, 1
	v_add3_u32 v0, v66, v0, s31
	v_lshrrev_b32_e32 v0, 16, v0
	v_and_or_b32 v56, v51, s71, v0
	v_bfe_u32 v0, v68, 16, 1
	v_bfe_u32 v51, v61, 16, 1
	v_add3_u32 v0, v68, v0, s31
	v_add3_u32 v51, v61, v51, s31
	ds_read2_b32 v[60:61], v49 offset0:20 offset1:28
	v_lshrrev_b32_e32 v0, 16, v0
	v_and_or_b32 v57, v51, s71, v0
	v_bfe_u32 v51, v63, 16, 1
	v_add3_u32 v51, v63, v51, s31
	ds_read2_b32 v[62:63], v49 offset0:150 offset1:158
	s_waitcnt lgkmcnt(0)
; #define LAS __attribute__((address_space(3)))
; __device__ __forceinline__ unsigned f2bf(float f) { unsigned u = __builtin_bit_cast(unsigned, f); return (u + 0x7fffu + ((u >> 16) & 1u)) >> 16; }
; __device__ __forceinline__ unsigned pk2(float lo, float hi) { return f2bf(lo) | (f2bf(hi) << 16); }
; __device__ __forceinline__ void tr_item(const float* __restrict__ W, int K, int N, bf16_t* __restrict__ WT, const float* __restrict__ gain, int mode, LAS float* scr, int item, int lane) {
;     ...
;     const int c = lane >> 3, nn = lane & 7;
; #pragma unroll
;     for (int j = 0; j < 8; ++j) { const int n = nn + 8 * j; const LAS float* s = scr + (8 * c) * 65 + n;
;         v4u o; o.x = pk2(s[0 * 65], s[1 * 65]); o.y = pk2(s[2 * 65], s[3 * 65]); o.z = pk2(s[4 * 65], s[5 * 65]); o.w = pk2(s[6 * 65], s[7 * 65]);
;         *(v4u*)(WT + (size_t)(n0 + n) * K + k0 + 8 * c) = o; }
;     asm volatile("s_waitcnt lgkmcnt(0)" ::: "memory");
	v_bfe_u32 v0, v60, 16, 1
	v_add3_u32 v0, v60, v0, s31
	v_lshrrev_b32_e32 v0, 16, v0
	v_and_or_b32 v58, v51, s71, v0
	v_bfe_u32 v0, v62, 16, 1
	v_add3_u32 v0, v62, v0, s31
	v_bfe_u32 v51, v65, 16, 1
	v_lshrrev_b32_e32 v0, 16, v0
	v_add3_u32 v51, v65, v51, s31
	v_and_or_b32 v59, v51, s71, v0
	v_or_b32_e32 v0, s5, v73
	v_lshlrev_b32_e32 v0, 12, v0
	v_lshl_add_u64 v[64:65], v[12:13], 0, v[0:1]
	flat_store_dwordx4 v[64:65], v[56:59]
	ds_read2_b32 v[64:65], v71 offset0:89 offset1:97
	v_bfe_u32 v0, v67, 16, 1
	v_add3_u32 v0, v67, v0, s31
	ds_read2_b32 v[66:67], v71 offset0:219 offset1:227
	v_lshrrev_b32_e32 v0, 16, v0
	s_waitcnt lgkmcnt(0)
	v_bfe_u32 v51, v64, 16, 1
	v_add3_u32 v51, v64, v51, s31
	v_and_or_b32 v56, v51, s71, v0
	v_bfe_u32 v0, v69, 16, 1
	v_add3_u32 v0, v69, v0, s31
	v_bfe_u32 v51, v66, 16, 1
	ds_read2_b32 v[68:69], v49 offset0:93 offset1:101
	v_lshrrev_b32_e32 v0, 16, v0
	v_add3_u32 v51, v66, v51, s31
	v_and_or_b32 v57, v51, s71, v0
	v_bfe_u32 v0, v61, 16, 1
	v_add3_u32 v0, v61, v0, s31
	ds_read2_b32 v[60:61], v49 offset0:223 offset1:231
	s_waitcnt lgkmcnt(0)
	v_bfe_u32 v51, v68, 16, 1
	v_lshrrev_b32_e32 v0, 16, v0
	v_add3_u32 v51, v68, v51, s31
	v_and_or_b32 v58, v51, s71, v0
	v_bfe_u32 v0, v63, 16, 1
	v_add3_u32 v0, v63, v0, s31
	v_bfe_u32 v51, v60, 16, 1
	v_lshrrev_b32_e32 v0, 16, v0
	v_add3_u32 v51, v60, v51, s31
	v_and_or_b32 v59, v51, s71, v0
	v_or_b32_e32 v0, s5, v74
	v_lshlrev_b32_e32 v0, 12, v0
	v_lshl_add_u64 v[62:63], v[12:13], 0, v[0:1]
	flat_store_dwordx4 v[62:63], v[56:59]
	ds_read2_b32 v[62:63], v71 offset0:32 offset1:40
	v_bfe_u32 v51, v65, 16, 1
	v_add3_u32 v51, v65, v51, s31
	ds_read2_b32 v[64:65], v71 offset0:162 offset1:170
	s_waitcnt lgkmcnt(0)
	v_bfe_u32 v0, v62, 16, 1
	v_add3_u32 v0, v62, v0, s31
	v_lshrrev_b32_e32 v0, 16, v0
	v_and_or_b32 v56, v51, s71, v0
	v_bfe_u32 v0, v64, 16, 1
	v_bfe_u32 v51, v67, 16, 1
	v_add3_u32 v0, v64, v0, s31
	v_add3_u32 v51, v67, v51, s31
	ds_read2_b32 v[66:67], v49 offset0:36 offset1:44
	v_lshrrev_b32_e32 v0, 16, v0
	v_and_or_b32 v57, v51, s71, v0
	v_bfe_u32 v51, v69, 16, 1
	v_add3_u32 v51, v69, v51, s31
	ds_read2_b32 v[68:69], v49 offset0:166 offset1:174
	s_waitcnt lgkmcnt(0)
	v_bfe_u32 v0, v66, 16, 1
	v_add3_u32 v0, v66, v0, s31
	v_lshrrev_b32_e32 v0, 16, v0
	v_and_or_b32 v58, v51, s71, v0
	v_bfe_u32 v0, v68, 16, 1
	v_add3_u32 v0, v68, v0, s31
	v_bfe_u32 v51, v61, 16, 1
	v_lshrrev_b32_e32 v0, 16, v0
	v_add3_u32 v51, v61, v51, s31
	v_and_or_b32 v59, v51, s71, v0
	v_or_b32_e32 v0, s5, v75
	v_lshlrev_b32_e32 v0, 12, v0
	v_lshl_add_u64 v[60:61], v[12:13], 0, v[0:1]
	flat_store_dwordx4 v[60:61], v[56:59]
	ds_read2_b32 v[60:61], v71 offset0:105 offset1:113
	v_bfe_u32 v0, v63, 16, 1
	v_add3_u32 v0, v63, v0, s31
	ds_read2_b32 v[62:63], v71 offset0:235 offset1:243
	v_lshrrev_b32_e32 v0, 16, v0
	s_waitcnt lgkmcnt(0)
	v_bfe_u32 v51, v60, 16, 1
	v_add3_u32 v51, v60, v51, s31
	v_and_or_b32 v56, v51, s71, v0
	v_bfe_u32 v0, v65, 16, 1
	v_add3_u32 v0, v65, v0, s31
	v_bfe_u32 v51, v62, 16, 1
	ds_read2_b32 v[64:65], v49 offset0:109 offset1:117
	v_lshrrev_b32_e32 v0, 16, v0
	v_add3_u32 v51, v62, v51, s31
	v_and_or_b32 v57, v51, s71, v0
	v_bfe_u32 v0, v67, 16, 1
	v_add3_u32 v0, v67, v0, s31
	ds_read2_b32 v[66:67], v49 offset0:239 offset1:247
	s_waitcnt lgkmcnt(0)
	v_bfe_u32 v51, v64, 16, 1
	v_lshrrev_b32_e32 v0, 16, v0
	v_add3_u32 v51, v64, v51, s31
	v_and_or_b32 v58, v51, s71, v0
	v_bfe_u32 v0, v69, 16, 1
	v_add3_u32 v0, v69, v0, s31
	v_bfe_u32 v49, v66, 16, 1
	v_lshrrev_b32_e32 v0, 16, v0
	v_add3_u32 v49, v66, v49, s31
	v_and_or_b32 v59, v49, s71, v0
	v_or_b32_e32 v0, s5, v76
	v_lshlrev_b32_e32 v0, 12, v0
	v_lshl_add_u64 v[68:69], v[12:13], 0, v[0:1]
	v_bfe_u32 v0, v48, 16, 1
	v_add3_u32 v0, v48, v0, s31
	v_bfe_u32 v48, v61, 16, 1
	v_lshrrev_b32_e32 v0, 16, v0
	v_add3_u32 v48, v61, v48, s31
	v_and_or_b32 v48, v48, s71, v0
	v_bfe_u32 v0, v50, 16, 1
	v_add3_u32 v0, v50, v0, s31
	v_bfe_u32 v49, v63, 16, 1
	v_lshrrev_b32_e32 v0, 16, v0
	v_add3_u32 v49, v63, v49, s31
	v_and_or_b32 v49, v49, s71, v0
	v_bfe_u32 v0, v52, 16, 1
	v_add3_u32 v0, v52, v0, s31
	v_bfe_u32 v50, v65, 16, 1
	v_lshrrev_b32_e32 v0, 16, v0
	v_add3_u32 v50, v65, v50, s31
	v_and_or_b32 v50, v50, s71, v0
	v_bfe_u32 v0, v54, 16, 1
	v_add3_u32 v0, v54, v0, s31
	v_bfe_u32 v51, v67, 16, 1
	v_lshrrev_b32_e32 v0, 16, v0
	v_add3_u32 v51, v67, v51, s31
	v_and_or_b32 v51, v51, s71, v0
	v_or_b32_e32 v0, s5, v77
	v_lshlrev_b32_e32 v0, 12, v0
	v_lshl_add_u64 v[52:53], v[12:13], 0, v[0:1]
	flat_store_dwordx4 v[52:53], v[48:51]
	ds_read2_b32 v[48:49], v79 offset1:65
	ds_read2_b32 v[50:51], v79 offset0:130 offset1:195
	flat_store_dwordx4 v[68:69], v[56:59]
	s_waitcnt lgkmcnt(0)
	v_bfe_u32 v0, v48, 16, 1
	v_add3_u32 v0, v48, v0, s31
	v_bfe_u32 v48, v49, 16, 1
	v_lshrrev_b32_e32 v0, 16, v0
	v_add3_u32 v48, v49, v48, s31
	v_and_or_b32 v48, v48, s71, v0
	v_bfe_u32 v0, v50, 16, 1
	v_add3_u32 v0, v50, v0, s31
	v_bfe_u32 v49, v51, 16, 1
	v_lshrrev_b32_e32 v0, 16, v0
	v_add3_u32 v49, v51, v49, s31
	v_and_or_b32 v49, v49, s71, v0
	v_add_u32_e32 v0, 0x400, v79
	ds_read2_b32 v[50:51], v0 offset0:4 offset1:69
	s_waitcnt lgkmcnt(0)
	v_bfe_u32 v52, v50, 16, 1
	v_add3_u32 v50, v50, v52, s31
	v_bfe_u32 v52, v51, 16, 1
	v_add3_u32 v51, v51, v52, s31
	ds_read2_b32 v[52:53], v0 offset0:134 offset1:199
	v_lshrrev_b32_e32 v50, 16, v50
	v_and_or_b32 v50, v51, s71, v50
	s_waitcnt lgkmcnt(0)
	v_bfe_u32 v0, v52, 16, 1
	v_add3_u32 v0, v52, v0, s31
	v_bfe_u32 v51, v53, 16, 1
	v_lshrrev_b32_e32 v0, 16, v0
	v_add3_u32 v51, v53, v51, s31
	v_and_or_b32 v51, v51, s71, v0
	v_or_b32_e32 v0, s5, v78
	v_lshlrev_b32_e32 v0, 12, v0
	v_lshl_add_u64 v[52:53], v[12:13], 0, v[0:1]
	flat_store_dwordx4 v[52:53], v[48:51]
	s_waitcnt lgkmcnt(0)

; #define LAS __attribute__((address_space(3)))
; __device__ __forceinline__ unsigned pk2(float lo, float hi) { return f2bf(lo) | (f2bf(hi) << 16); }
; __device__ __forceinline__ void tr_item(const float* __restrict__ W, int K, int N, bf16_t* __restrict__ WT, const float* __restrict__ gain, int mode, LAS float* scr, int item, int lane) {
;     ...
; #pragma unroll 8
;     for (int i = 0; i < 16; ++i) { const int kk = 4 * i + lk; const float g = gain ? gain[k0 + kk] * cs : cs; const f32x4 v = __builtin_nontemporal_load((const f32x4*)(W + (size_t)(k0 + kk) * N + src0 + ln));
;         LAS float* d = scr + kk * 65 + ln; d[0] = v.x * g; d[1] = v.y * g; d[2] = v.z * g; d[3] = v.w * g; }
;     asm volatile("s_waitcnt lgkmcnt(0)" ::: "memory");
;     const int c = lane >> 3, nn = lane & 7;
; #pragma unroll
;     for (int j = 0; j < 8; ++j) { const int n = nn + 8 * j; const LAS float* s = scr + (8 * c) * 65 + n;
;         v4u o; o.x = pk2(s[0 * 65], s[1 * 65]); o.y = pk2(s[2 * 65], s[3 * 65]); o.z = pk2(s[4 * 65], s[5 * 65]); o.w = pk2(s[6 * 65], s[7 * 65]);
;         *(v4u*)(WT + (size_t)(n0 + n) * K + k0 + 8 * c) = o; }
.LBB0_380:
	v_lshl_add_u64 v[64:65], v[62:63], 0, s[2:3]
	global_load_dwordx4 v[100:103], v[64:65], off nt
	v_lshl_add_u64 v[66:67], v[60:61], 0, s[2:3]
	global_load_dwordx4 v[104:107], v[66:67], off nt
	v_lshl_add_u64 v[64:65], v[58:59], 0, s[2:3]
	global_load_dwordx4 v[108:111], v[64:65], off nt
	v_lshl_add_u64 v[66:67], v[56:57], 0, s[2:3]
	global_load_dwordx4 v[112:115], v[66:67], off nt
	v_lshl_add_u64 v[64:65], v[54:55], 0, s[2:3]
	global_load_dwordx4 v[116:119], v[64:65], off nt
	v_lshl_add_u64 v[66:67], v[52:53], 0, s[2:3]
	global_load_dwordx4 v[120:123], v[66:67], off nt
	v_lshl_add_u64 v[64:65], v[50:51], 0, s[2:3]
	global_load_dwordx4 v[124:127], v[64:65], off nt
	v_lshl_add_u64 v[66:67], v[48:49], 0, s[2:3]
	global_load_dwordx4 v[128:131], v[66:67], off nt
	s_add_u32 s2, s2, 0x40000
	s_addc_u32 s3, s3, 0
	s_waitcnt vmcnt(7)
	ds_write2_b32 v0, v100, v101 offset1:1
	ds_write2_b32 v0, v102, v103 offset0:2 offset1:3
	s_waitcnt vmcnt(6)
	v_add_u32_e32 v68, 0x410, v0
	v_add_u32_e32 v64, 0x418, v0
	ds_write2_b32 v68, v104, v105 offset1:1
	ds_write2_b32 v64, v106, v107 offset1:1
	s_waitcnt vmcnt(5)
	v_add_u32_e32 v68, 0x820, v0
	v_add_u32_e32 v64, 0x828, v0
	ds_write2_b32 v68, v108, v109 offset1:1
	ds_write2_b32 v64, v110, v111 offset1:1
	s_waitcnt vmcnt(4)
	v_add_u32_e32 v68, 0xc30, v0
	v_add_u32_e32 v64, 0xc38, v0
	ds_write2_b32 v68, v112, v113 offset1:1
	ds_write2_b32 v64, v114, v115 offset1:1
	s_waitcnt vmcnt(3)
	v_add_u32_e32 v68, 0x1040, v0
	v_add_u32_e32 v64, 0x1048, v0
	ds_write2_b32 v68, v116, v117 offset1:1
	ds_write2_b32 v64, v118, v119 offset1:1
	s_waitcnt vmcnt(2)
	v_add_u32_e32 v68, 0x1450, v0
	v_add_u32_e32 v64, 0x1458, v0
	ds_write2_b32 v68, v120, v121 offset1:1
	ds_write2_b32 v64, v122, v123 offset1:1
	s_waitcnt vmcnt(1)
	v_add_u32_e32 v68, 0x1860, v0
	v_add_u32_e32 v64, 0x1868, v0
	ds_write2_b32 v68, v124, v125 offset1:1
	ds_write2_b32 v64, v126, v127 offset1:1
	s_waitcnt vmcnt(0)
	v_add_u32_e32 v68, 0x1c70, v0
	v_add_u32_e32 v64, 0x1c78, v0
	ds_write2_b32 v68, v128, v129 offset1:1
	ds_write2_b32 v64, v130, v131 offset1:1
	v_add_u32_e32 v0, 0x2080, v0
	s_cmp_lg_u32 s2, 0x80000
	s_cbranch_scc1 .LBB0_380
	s_waitcnt lgkmcnt(0)
	ds_read2_b32 v[48:49], v71 offset0:48 offset1:65
	ds_read2_b32 v[60:61], v71 offset1:8
	s_movk_i32 s6, 0x5f
	s_waitcnt lgkmcnt(1)
	v_bfe_u32 v50, v49, 16, 1
	v_add3_u32 v49, v49, v50, s31
	ds_read2_b32 v[62:63], v71 offset0:130 offset1:138
	ds_read2_b32 v[50:51], v71 offset0:178 offset1:195
	s_waitcnt lgkmcnt(2)
	v_bfe_u32 v0, v60, 16, 1
	v_add3_u32 v0, v60, v0, s31
	v_lshrrev_b32_e32 v0, 16, v0
	v_and_or_b32 v56, v49, s71, v0
	s_waitcnt lgkmcnt(1)
	v_bfe_u32 v0, v62, 16, 1
	v_add3_u32 v0, v62, v0, s31
	s_waitcnt lgkmcnt(0)
	v_bfe_u32 v49, v51, 16, 1
	v_lshrrev_b32_e32 v0, 16, v0
	v_add3_u32 v49, v51, v49, s31
	v_and_or_b32 v57, v49, s71, v0
	v_add_u32_e32 v49, 0x400, v71
	ds_read2_b32 v[64:65], v49 offset0:4 offset1:12
	ds_read2_b32 v[52:53], v49 offset0:52 offset1:69
	ds_read2_b32 v[66:67], v49 offset0:134 offset1:142
	ds_read2_b32 v[54:55], v49 offset0:182 offset1:199
	s_waitcnt lgkmcnt(3)
	v_bfe_u32 v0, v64, 16, 1
	v_add3_u32 v0, v64, v0, s31
	s_waitcnt lgkmcnt(2)
	v_bfe_u32 v51, v53, 16, 1
	v_lshrrev_b32_e32 v0, 16, v0
	v_add3_u32 v51, v53, v51, s31
	v_and_or_b32 v58, v51, s71, v0
	s_waitcnt lgkmcnt(1)
	v_bfe_u32 v0, v66, 16, 1
	v_add3_u32 v0, v66, v0, s31
	s_waitcnt lgkmcnt(0)
	v_bfe_u32 v51, v55, 16, 1
	v_lshrrev_b32_e32 v0, 16, v0
	v_add3_u32 v51, v55, v51, s31
	v_and_or_b32 v59, v51, s71, v0
	v_or_b32_e32 v0, s5, v3
	v_mul_u32_u24_e32 v0, 0x1600, v0
	v_lshlrev_b32_e32 v0, 1, v0
	v_lshl_add_u64 v[68:69], v[14:15], 0, v[0:1]
	flat_store_dwordx4 v[68:69], v[56:59]
	ds_read2_b32 v[68:69], v71 offset0:73 offset1:81
	v_bfe_u32 v0, v61, 16, 1
	v_add3_u32 v0, v61, v0, s31
	ds_read2_b32 v[60:61], v71 offset0:203 offset1:211
	v_lshrrev_b32_e32 v0, 16, v0
	s_waitcnt lgkmcnt(0)
	v_bfe_u32 v51, v68, 16, 1
	v_add3_u32 v51, v68, v51, s31
	v_and_or_b32 v56, v51, s71, v0
	v_bfe_u32 v0, v63, 16, 1
	v_add3_u32 v0, v63, v0, s31
	v_bfe_u32 v51, v60, 16, 1
	ds_read2_b32 v[62:63], v49 offset0:77 offset1:85
	v_lshrrev_b32_e32 v0, 16, v0
	v_add3_u32 v51, v60, v51, s31
	v_and_or_b32 v57, v51, s71, v0
	v_bfe_u32 v0, v65, 16, 1
	v_add3_u32 v0, v65, v0, s31
	ds_read2_b32 v[64:65], v49 offset0:207 offset1:215
	s_waitcnt lgkmcnt(0)
	v_bfe_u32 v51, v62, 16, 1
	v_lshrrev_b32_e32 v0, 16, v0
	v_add3_u32 v51, v62, v51, s31
	v_and_or_b32 v58, v51, s71, v0
	v_bfe_u32 v0, v67, 16, 1
	v_add3_u32 v0, v67, v0, s31
	v_bfe_u32 v51, v64, 16, 1
	v_lshrrev_b32_e32 v0, 16, v0
	v_add3_u32 v51, v64, v51, s31
	v_and_or_b32 v59, v51, s71, v0
	v_or_b32_e32 v0, s5, v72
	v_mul_u32_u24_e32 v0, 0x1600, v0
	v_lshlrev_b32_e32 v0, 1, v0
	v_lshl_add_u64 v[66:67], v[14:15], 0, v[0:1]
	flat_store_dwordx4 v[66:67], v[56:59]
	ds_read2_b32 v[66:67], v71 offset0:16 offset1:24
	v_bfe_u32 v51, v69, 16, 1
	v_add3_u32 v51, v69, v51, s31
	ds_read2_b32 v[68:69], v71 offset0:146 offset1:154
	s_waitcnt lgkmcnt(0)
	v_bfe_u32 v0, v66, 16, 1
	v_add3_u32 v0, v66, v0, s31
	v_lshrrev_b32_e32 v0, 16, v0
	v_and_or_b32 v56, v51, s71, v0
	v_bfe_u32 v0, v68, 16, 1
	v_bfe_u32 v51, v61, 16, 1
	v_add3_u32 v0, v68, v0, s31
	v_add3_u32 v51, v61, v51, s31
	ds_read2_b32 v[60:61], v49 offset0:20 offset1:28
	v_lshrrev_b32_e32 v0, 16, v0
	v_and_or_b32 v57, v51, s71, v0
	v_bfe_u32 v51, v63, 16, 1
	v_add3_u32 v51, v63, v51, s31
	ds_read2_b32 v[62:63], v49 offset0:150 offset1:158
	s_waitcnt lgkmcnt(0)
; #define LAS __attribute__((address_space(3)))
; __device__ __forceinline__ unsigned f2bf(float f) { unsigned u = __builtin_bit_cast(unsigned, f); return (u + 0x7fffu + ((u >> 16) & 1u)) >> 16; }
; __device__ __forceinline__ unsigned pk2(float lo, float hi) { return f2bf(lo) | (f2bf(hi) << 16); }
; __device__ __forceinline__ void tr_item(const float* __restrict__ W, int K, int N, bf16_t* __restrict__ WT, const float* __restrict__ gain, int mode, LAS float* scr, int item, int lane) {
;     ...
;     const int c = lane >> 3, nn = lane & 7;
; #pragma unroll
;     for (int j = 0; j < 8; ++j) { const int n = nn + 8 * j; const LAS float* s = scr + (8 * c) * 65 + n;
;         v4u o; o.x = pk2(s[0 * 65], s[1 * 65]); o.y = pk2(s[2 * 65], s[3 * 65]); o.z = pk2(s[4 * 65], s[5 * 65]); o.w = pk2(s[6 * 65], s[7 * 65]);
;         *(v4u*)(WT + (size_t)(n0 + n) * K + k0 + 8 * c) = o; }
;     asm volatile("s_waitcnt lgkmcnt(0)" ::: "memory");
	v_bfe_u32 v0, v60, 16, 1
	v_add3_u32 v0, v60, v0, s31
	v_lshrrev_b32_e32 v0, 16, v0
	v_and_or_b32 v58, v51, s71, v0
	v_bfe_u32 v0, v62, 16, 1
	v_add3_u32 v0, v62, v0, s31
	v_bfe_u32 v51, v65, 16, 1
	v_lshrrev_b32_e32 v0, 16, v0
	v_add3_u32 v51, v65, v51, s31
	v_and_or_b32 v59, v51, s71, v0
	v_or_b32_e32 v0, s5, v73
	v_mul_u32_u24_e32 v0, 0x1600, v0
	v_lshlrev_b32_e32 v0, 1, v0
	v_lshl_add_u64 v[64:65], v[14:15], 0, v[0:1]
	flat_store_dwordx4 v[64:65], v[56:59]
	ds_read2_b32 v[64:65], v71 offset0:89 offset1:97
	v_bfe_u32 v0, v67, 16, 1
	v_add3_u32 v0, v67, v0, s31
	ds_read2_b32 v[66:67], v71 offset0:219 offset1:227
	v_lshrrev_b32_e32 v0, 16, v0
	s_waitcnt lgkmcnt(0)
	v_bfe_u32 v51, v64, 16, 1
	v_add3_u32 v51, v64, v51, s31
	v_and_or_b32 v56, v51, s71, v0
	v_bfe_u32 v0, v69, 16, 1
	v_add3_u32 v0, v69, v0, s31
	v_bfe_u32 v51, v66, 16, 1
	ds_read2_b32 v[68:69], v49 offset0:93 offset1:101
	v_lshrrev_b32_e32 v0, 16, v0
	v_add3_u32 v51, v66, v51, s31
	v_and_or_b32 v57, v51, s71, v0
	v_bfe_u32 v0, v61, 16, 1
	v_add3_u32 v0, v61, v0, s31
	ds_read2_b32 v[60:61], v49 offset0:223 offset1:231
	s_waitcnt lgkmcnt(0)
	v_bfe_u32 v51, v68, 16, 1
	v_lshrrev_b32_e32 v0, 16, v0
	v_add3_u32 v51, v68, v51, s31
	v_and_or_b32 v58, v51, s71, v0
	v_bfe_u32 v0, v63, 16, 1
	v_add3_u32 v0, v63, v0, s31
	v_bfe_u32 v51, v60, 16, 1
	v_lshrrev_b32_e32 v0, 16, v0
	v_add3_u32 v51, v60, v51, s31
	v_and_or_b32 v59, v51, s71, v0
	v_or_b32_e32 v0, s5, v74
	v_mul_u32_u24_e32 v0, 0x1600, v0
	v_lshlrev_b32_e32 v0, 1, v0
	v_lshl_add_u64 v[62:63], v[14:15], 0, v[0:1]
	flat_store_dwordx4 v[62:63], v[56:59]
	ds_read2_b32 v[62:63], v71 offset0:32 offset1:40
	v_bfe_u32 v51, v65, 16, 1
	v_add3_u32 v51, v65, v51, s31
	ds_read2_b32 v[64:65], v71 offset0:162 offset1:170
	s_waitcnt lgkmcnt(0)
	v_bfe_u32 v0, v62, 16, 1
	v_add3_u32 v0, v62, v0, s31
	v_lshrrev_b32_e32 v0, 16, v0
	v_and_or_b32 v56, v51, s71, v0
	v_bfe_u32 v0, v64, 16, 1
	v_bfe_u32 v51, v67, 16, 1
	v_add3_u32 v0, v64, v0, s31
	v_add3_u32 v51, v67, v51, s31
	ds_read2_b32 v[66:67], v49 offset0:36 offset1:44
	v_lshrrev_b32_e32 v0, 16, v0
	v_and_or_b32 v57, v51, s71, v0
	v_bfe_u32 v51, v69, 16, 1
	v_add3_u32 v51, v69, v51, s31
	ds_read2_b32 v[68:69], v49 offset0:166 offset1:174
	s_waitcnt lgkmcnt(0)
	v_bfe_u32 v0, v66, 16, 1
	v_add3_u32 v0, v66, v0, s31
	v_lshrrev_b32_e32 v0, 16, v0
	v_and_or_b32 v58, v51, s71, v0
	v_bfe_u32 v0, v68, 16, 1
	v_add3_u32 v0, v68, v0, s31
	v_bfe_u32 v51, v61, 16, 1
	v_lshrrev_b32_e32 v0, 16, v0
	v_add3_u32 v51, v61, v51, s31
	v_and_or_b32 v59, v51, s71, v0
	v_or_b32_e32 v0, s5, v75
	v_mul_u32_u24_e32 v0, 0x1600, v0
	v_lshlrev_b32_e32 v0, 1, v0
	v_lshl_add_u64 v[60:61], v[14:15], 0, v[0:1]
	flat_store_dwordx4 v[60:61], v[56:59]
	ds_read2_b32 v[60:61], v71 offset0:105 offset1:113
	v_bfe_u32 v0, v63, 16, 1
	v_add3_u32 v0, v63, v0, s31
	ds_read2_b32 v[62:63], v71 offset0:235 offset1:243
	v_lshrrev_b32_e32 v0, 16, v0
	s_waitcnt lgkmcnt(0)
	v_bfe_u32 v51, v60, 16, 1
	v_add3_u32 v51, v60, v51, s31
	v_and_or_b32 v56, v51, s71, v0
	v_bfe_u32 v0, v65, 16, 1
	v_add3_u32 v0, v65, v0, s31
	v_bfe_u32 v51, v62, 16, 1
	ds_read2_b32 v[64:65], v49 offset0:109 offset1:117
	v_lshrrev_b32_e32 v0, 16, v0
	v_add3_u32 v51, v62, v51, s31
	v_and_or_b32 v57, v51, s71, v0
	v_bfe_u32 v0, v67, 16, 1
	v_add3_u32 v0, v67, v0, s31
	ds_read2_b32 v[66:67], v49 offset0:239 offset1:247
	s_waitcnt lgkmcnt(0)
	v_bfe_u32 v51, v64, 16, 1
	v_lshrrev_b32_e32 v0, 16, v0
	v_add3_u32 v51, v64, v51, s31
	v_and_or_b32 v58, v51, s71, v0
	v_bfe_u32 v0, v69, 16, 1
	v_add3_u32 v0, v69, v0, s31
	v_bfe_u32 v49, v66, 16, 1
	v_lshrrev_b32_e32 v0, 16, v0
	v_add3_u32 v49, v66, v49, s31
	v_and_or_b32 v59, v49, s71, v0
	v_or_b32_e32 v0, s5, v76
	v_mul_u32_u24_e32 v0, 0x1600, v0
	v_lshlrev_b32_e32 v0, 1, v0
	v_lshl_add_u64 v[68:69], v[14:15], 0, v[0:1]
	v_bfe_u32 v0, v48, 16, 1
	v_add3_u32 v0, v48, v0, s31
	v_bfe_u32 v48, v61, 16, 1
	v_lshrrev_b32_e32 v0, 16, v0
	v_add3_u32 v48, v61, v48, s31
	v_and_or_b32 v48, v48, s71, v0
	v_bfe_u32 v0, v50, 16, 1
	v_add3_u32 v0, v50, v0, s31
	v_bfe_u32 v49, v63, 16, 1
	v_lshrrev_b32_e32 v0, 16, v0
	v_add3_u32 v49, v63, v49, s31
	v_and_or_b32 v49, v49, s71, v0
	v_bfe_u32 v0, v52, 16, 1
	v_add3_u32 v0, v52, v0, s31
	v_bfe_u32 v50, v65, 16, 1
	v_lshrrev_b32_e32 v0, 16, v0
	v_add3_u32 v50, v65, v50, s31
	v_and_or_b32 v50, v50, s71, v0
	v_bfe_u32 v0, v54, 16, 1
	v_add3_u32 v0, v54, v0, s31
	v_bfe_u32 v51, v67, 16, 1
	v_lshrrev_b32_e32 v0, 16, v0
	v_add3_u32 v51, v67, v51, s31
	v_and_or_b32 v51, v51, s71, v0
	v_or_b32_e32 v0, s5, v77
	v_mul_u32_u24_e32 v0, 0x1600, v0
	v_lshlrev_b32_e32 v0, 1, v0
	v_lshl_add_u64 v[52:53], v[14:15], 0, v[0:1]
	flat_store_dwordx4 v[68:69], v[56:59]
	flat_store_dwordx4 v[52:53], v[48:51]
	ds_read2_b32 v[48:49], v79 offset1:65
	ds_read2_b32 v[50:51], v79 offset0:130 offset1:195
	s_waitcnt lgkmcnt(0)
	v_bfe_u32 v0, v48, 16, 1
	v_add3_u32 v0, v48, v0, s31
	v_bfe_u32 v48, v49, 16, 1
	v_lshrrev_b32_e32 v0, 16, v0
	v_add3_u32 v48, v49, v48, s31
	v_and_or_b32 v48, v48, s71, v0
	v_bfe_u32 v0, v50, 16, 1
	v_add3_u32 v0, v50, v0, s31
	v_bfe_u32 v49, v51, 16, 1
	v_lshrrev_b32_e32 v0, 16, v0
	v_add3_u32 v49, v51, v49, s31
	v_and_or_b32 v49, v49, s71, v0
	v_add_u32_e32 v0, 0x400, v79
	ds_read2_b32 v[50:51], v0 offset0:4 offset1:69
	s_waitcnt lgkmcnt(0)
	v_bfe_u32 v52, v50, 16, 1
	v_add3_u32 v50, v50, v52, s31
	v_bfe_u32 v52, v51, 16, 1
	v_add3_u32 v51, v51, v52, s31
	ds_read2_b32 v[52:53], v0 offset0:134 offset1:199
	v_lshrrev_b32_e32 v50, 16, v50
	v_and_or_b32 v50, v51, s71, v50
	s_waitcnt lgkmcnt(0)
	v_bfe_u32 v0, v52, 16, 1
	v_add3_u32 v0, v52, v0, s31
	v_bfe_u32 v51, v53, 16, 1
	v_lshrrev_b32_e32 v0, 16, v0
	v_add3_u32 v51, v53, v51, s31
	v_and_or_b32 v51, v51, s71, v0
	v_or_b32_e32 v0, s5, v78
	v_mul_u32_u24_e32 v0, 0x1600, v0
	v_lshlrev_b32_e32 v0, 1, v0
	v_lshl_add_u64 v[52:53], v[14:15], 0, v[0:1]
	flat_store_dwordx4 v[52:53], v[48:51]
	s_waitcnt lgkmcnt(0)
